# v27: v11 + P13 W2-to-LDS fill de-serialised (eighth load issued with the first seven instead of after their waits)
# speedup vs baseline: 1.0060x; 1.0060x over previous
; #define LAS __attribute__((address_space(3)))
; DI void phase_precompute(const Params& p, ldsp lds, int tid) {
;   for (int i = tid; i < 4096; i += 512) *(LAS float*)(lds + i * 4) = p.in[11][i];
;   __syncthreads();
.LBB0_342:
	s_or_b64 exec, exec, s[4:5]
	s_load_dwordx4 s[52:55], s[72:73], 0x58
	v_lshlrev_b32_e32 v2, 2, v212
	v_mov_b32_e32 v3, 0
	s_movk_i32 s0, 0x1000
	v_or_b32_e32 v9, 0xc00, v212
	s_waitcnt lgkmcnt(0)
	v_lshl_add_u64 v[0:1], s[52:53], 0, v[2:3]
	v_add_co_u32_e32 v4, vcc, s0, v0
	s_nop 1
	v_addc_co_u32_e32 v5, vcc, 0, v1, vcc
	v_add_co_u32_e32 v6, vcc, 0x2000, v0
	s_barrier
	v_or_b32_e32 v3, 0x1000, v2
	v_or_b32_e32 v8, 0x2000, v2
	v_addc_co_u32_e32 v7, vcc, 0, v1, vcc
	v_lshlrev_b32_e32 v10, 2, v9
	global_load_dword v11, v2, s[52:53]
	global_load_dword v12, v2, s[52:53] offset:2048
	global_load_dword v13, v3, s[52:53]
	global_load_dword v14, v[4:5], off offset:2048
	global_load_dword v15, v8, s[52:53]
	global_load_dword v16, v[6:7], off offset:2048
	global_load_dword v17, v10, s[52:53]
	v_add_co_u32_e32 v18, vcc, 0x3000, v0
	s_nop 1
	v_addc_co_u32_e32 v19, vcc, 0, v1, vcc
	global_load_dword v18, v[18:19], off offset:2048
	s_movk_i32 s0, 0xe00
	v_add_u32_e32 v2, 16, v2
	v_cmp_gt_u32_e32 vcc, s0, v9
	v_add_u32_e32 v3, 16, v3
	v_add_u32_e32 v4, 16, v8
	v_add_u32_e32 v5, 16, v10
	s_waitcnt vmcnt(6)
	ds_write2st64_b32 v2, v11, v12 offset1:8
	s_waitcnt vmcnt(5)
	ds_write_b32 v3, v13
	s_waitcnt vmcnt(3)
	ds_write_b32 v4, v15
	s_waitcnt vmcnt(2)
	ds_write2st64_b32 v2, v14, v16 offset0:24 offset1:40
	s_waitcnt vmcnt(1)
	ds_write_b32 v5, v17
	s_and_saveexec_b64 s[4:5], vcc
	s_cbranch_execz .LBB0_344
	v_lshl_add_u32 v1, v212, 2, 16
	s_waitcnt vmcnt(0)
	ds_write_b32 v1, v18 offset:14336
